# fused final-norm epilogue: v_permlane32_swap so every f32 output store writes 64 contiguous bytes per row instead of 16-byte pieces at 32-byte stride
# speedup vs baseline: 1.0064x; 1.0051x over previous
;     __device__ __forceinline__ void operator()(f32x4 (&acc)[2][2][4][2], const Unit& u, int wr, int wc, int fr, int fq) const {
;     ...
;         f32x4 gg[2][2];
; #pragma unroll
;         for (int bj = 0; bj < 2; ++bj) { gg[bj][0] = *(const f32x4*)(gfin + col0 + bj * HALF); gg[bj][1] = *(const f32x4*)(gfin + col0 + bj * HALF + 4); }
; #pragma unroll
;         for (int ai = 0; ai < 2; ++ai)
; #pragma unroll
;             for (int m = 0; m < 4; ++m) { const int rl = ai * HALF + wr * 64 + m * 16 + fr; const float rs = rstab[rl]; float* orow = out + (size_t)(u.pm * BM + rl) * D + col0;
; #pragma unroll
;                 for (int bj = 0; bj < 2; ++bj) { *(f32x4*)(orow + bj * HALF) = acc[ai][bj][m][0] * gg[bj][0] * rs; *(f32x4*)(orow + bj * HALF + 4) = acc[ai][bj][m][1] * gg[bj][1] * rs; } }
.LBB0_238:
	s_or_b64 exec, exec, s[4:5]
	v_readlane_b32 s4, v255, 0
	v_lshlrev_b64 v[146:147], 2, v[204:205]
	v_readlane_b32 s5, v255, 1
	s_waitcnt lgkmcnt(0)
	s_barrier
	v_lshlrev_b64 v[148:149], 12, v[202:203]
	v_lshl_add_u64 v[2:3], s[4:5], 0, v[146:147]
	flat_load_dwordx4 v[14:17], v[2:3]
	flat_load_dwordx4 v[10:13], v[2:3] offset:16
	flat_load_dwordx4 v[6:9], v[2:3] offset:512
	s_nop 0
	flat_load_dwordx4 v[2:5], v[2:3] offset:528
	ds_read_b32 v156, v217
	v_lshl_add_u64 v[148:149], s[34:35], 0, v[148:149]
	v_bfe_u32 v157, v226, 5, 1
	v_mul_u32_u24_e32 v157, 0x50, v157
	v_sub_u32_e32 v146, v146, v157
	v_add_u32_e32 v146, 16, v146
	v_lshl_add_u64 v[148:149], v[148:149], 0, v[146:147]
	v_add_u32_e32 v150, s51, v210
	v_ashrrev_i32_e32 v151, 31, v150
	v_lshlrev_b64 v[150:151], 12, v[150:151]
	v_lshl_add_u64 v[150:151], s[34:35], 0, v[150:151]
	v_lshl_add_u64 v[150:151], v[150:151], 0, v[146:147]
	v_add_u32_e32 v152, s51, v211
	v_ashrrev_i32_e32 v153, 31, v152
	v_lshlrev_b64 v[152:153], 12, v[152:153]
	v_lshl_add_u64 v[152:153], s[34:35], 0, v[152:153]
	v_lshl_add_u64 v[152:153], v[152:153], 0, v[146:147]
	v_add_u32_e32 v154, s51, v212
	v_ashrrev_i32_e32 v155, 31, v154
	v_lshlrev_b64 v[154:155], 12, v[154:155]
	v_lshl_add_u64 v[154:155], s[34:35], 0, v[154:155]
	v_lshl_add_u64 v[154:155], v[154:155], 0, v[146:147]
	s_and_b64 vcc, exec, s[8:9]
	s_mov_b64 s[4:5], -1
	s_waitcnt vmcnt(0) lgkmcnt(0)
	v_pk_mul_f32 v[128:129], v[128:129], v[16:17]
	v_pk_mul_f32 v[126:127], v[126:127], v[14:15]
	v_pk_mul_f32 v[124:125], v[124:125], v[12:13]
	v_pk_mul_f32 v[122:123], v[122:123], v[10:11]
	v_pk_mul_f32 v[120:121], v[120:121], v[8:9]
	v_pk_mul_f32 v[118:119], v[118:119], v[6:7]
	v_pk_mul_f32 v[116:117], v[116:117], v[4:5]
	v_pk_mul_f32 v[114:115], v[114:115], v[2:3]
	v_pk_mul_f32 v[170:171], v[96:97], v[16:17]
	v_pk_mul_f32 v[172:173], v[94:95], v[14:15]
	v_pk_mul_f32 v[94:95], v[126:127], v[156:157] op_sel_hi:[1,0]
	v_pk_mul_f32 v[96:97], v[128:129], v[156:157] op_sel_hi:[1,0]
	v_pk_mul_f32 v[158:159], v[108:109], v[12:13]
	v_pk_mul_f32 v[160:161], v[106:107], v[10:11]
	v_pk_mul_f32 v[162:163], v[104:105], v[8:9]
	v_pk_mul_f32 v[164:165], v[102:103], v[6:7]
	v_pk_mul_f32 v[166:167], v[100:101], v[4:5]
	v_pk_mul_f32 v[168:169], v[98:99], v[2:3]
	v_pk_mul_f32 v[98:99], v[122:123], v[156:157] op_sel_hi:[1,0]
	v_pk_mul_f32 v[100:101], v[124:125], v[156:157] op_sel_hi:[1,0]
	v_pk_mul_f32 v[102:103], v[118:119], v[156:157] op_sel_hi:[1,0]
	v_pk_mul_f32 v[104:105], v[120:121], v[156:157] op_sel_hi:[1,0]
	v_pk_mul_f32 v[106:107], v[114:115], v[156:157] op_sel_hi:[1,0]
	v_pk_mul_f32 v[108:109], v[116:117], v[156:157] op_sel_hi:[1,0]
	s_nop 1
	v_permlane32_swap_b32_e32 v98, v94
	v_permlane32_swap_b32_e32 v99, v95
	v_permlane32_swap_b32_e32 v100, v96
	v_permlane32_swap_b32_e32 v101, v97
	v_permlane32_swap_b32_e32 v106, v102
	v_permlane32_swap_b32_e32 v107, v103
	v_permlane32_swap_b32_e32 v108, v104
	v_permlane32_swap_b32_e32 v109, v105
	flat_store_dwordx4 v[148:149], v[98:101]
	flat_store_dwordx4 v[148:149], v[94:97] offset:64
	flat_store_dwordx4 v[148:149], v[106:109] offset:512
	flat_store_dwordx4 v[148:149], v[102:105] offset:576
	ds_read_b32 v98, v218
	v_pk_mul_f32 v[112:113], v[112:113], v[16:17]
	v_pk_mul_f32 v[110:111], v[110:111], v[14:15]
	v_pk_mul_f32 v[106:107], v[88:89], v[8:9]
	v_pk_mul_f32 v[108:109], v[86:87], v[6:7]
	s_waitcnt lgkmcnt(0)
	v_pk_mul_f32 v[88:89], v[112:113], v[98:99] op_sel_hi:[1,0]
	v_pk_mul_f32 v[86:87], v[110:111], v[98:99] op_sel_hi:[1,0]
	v_pk_mul_f32 v[102:103], v[92:93], v[12:13]
	v_pk_mul_f32 v[104:105], v[90:91], v[10:11]
	v_pk_mul_f32 v[92:93], v[158:159], v[98:99] op_sel_hi:[1,0]
	v_pk_mul_f32 v[90:91], v[160:161], v[98:99] op_sel_hi:[1,0]
	v_pk_mul_f32 v[96:97], v[162:163], v[98:99] op_sel_hi:[1,0]
	v_pk_mul_f32 v[94:95], v[164:165], v[98:99] op_sel_hi:[1,0]
	v_pk_mul_f32 v[100:101], v[166:167], v[98:99] op_sel_hi:[1,0]
	v_pk_mul_f32 v[98:99], v[168:169], v[98:99] op_sel_hi:[1,0]
	s_nop 1
	v_permlane32_swap_b32_e32 v90, v86
	v_permlane32_swap_b32_e32 v91, v87
	v_permlane32_swap_b32_e32 v92, v88
	v_permlane32_swap_b32_e32 v93, v89
	v_permlane32_swap_b32_e32 v98, v94
	v_permlane32_swap_b32_e32 v99, v95
	v_permlane32_swap_b32_e32 v100, v96
	v_permlane32_swap_b32_e32 v101, v97
	flat_store_dwordx4 v[150:151], v[90:93]
	flat_store_dwordx4 v[150:151], v[86:89] offset:64
	flat_store_dwordx4 v[150:151], v[98:101] offset:512
	flat_store_dwordx4 v[150:151], v[94:97] offset:576
	ds_read_b32 v90, v219
	v_pk_mul_f32 v[92:93], v[84:85], v[4:5]
	v_pk_mul_f32 v[94:95], v[82:83], v[2:3]
	v_pk_mul_f32 v[96:97], v[80:81], v[16:17]
	v_pk_mul_f32 v[98:99], v[78:79], v[14:15]
	s_waitcnt lgkmcnt(0)
	v_pk_mul_f32 v[80:81], v[170:171], v[90:91] op_sel_hi:[1,0]
	v_pk_mul_f32 v[78:79], v[172:173], v[90:91] op_sel_hi:[1,0]
	v_pk_mul_f32 v[84:85], v[102:103], v[90:91] op_sel_hi:[1,0]
	v_pk_mul_f32 v[82:83], v[104:105], v[90:91] op_sel_hi:[1,0]
	v_pk_mul_f32 v[88:89], v[106:107], v[90:91] op_sel_hi:[1,0]
	v_pk_mul_f32 v[86:87], v[108:109], v[90:91] op_sel_hi:[1,0]
	v_pk_mul_f32 v[92:93], v[92:93], v[90:91] op_sel_hi:[1,0]
	v_pk_mul_f32 v[90:91], v[94:95], v[90:91] op_sel_hi:[1,0]
	s_nop 1
	v_permlane32_swap_b32_e32 v82, v78
	v_permlane32_swap_b32_e32 v83, v79
	v_permlane32_swap_b32_e32 v84, v80
	v_permlane32_swap_b32_e32 v85, v81
	v_permlane32_swap_b32_e32 v90, v86
	v_permlane32_swap_b32_e32 v91, v87
	v_permlane32_swap_b32_e32 v92, v88
	v_permlane32_swap_b32_e32 v93, v89
	flat_store_dwordx4 v[152:153], v[82:85]
	flat_store_dwordx4 v[152:153], v[78:81] offset:64
	flat_store_dwordx4 v[152:153], v[90:93] offset:512
	flat_store_dwordx4 v[152:153], v[86:89] offset:576
	ds_read_b32 v82, v240
	v_pk_mul_f32 v[68:69], v[68:69], v[4:5]
	v_pk_mul_f32 v[66:67], v[66:67], v[2:3]
	v_pk_mul_f32 v[76:77], v[76:77], v[12:13]
	v_pk_mul_f32 v[74:75], v[74:75], v[10:11]
	v_pk_mul_f32 v[78:79], v[72:73], v[8:9]
	v_pk_mul_f32 v[84:85], v[70:71], v[6:7]
	s_waitcnt lgkmcnt(0)
;     __device__ __forceinline__ void operator()(f32x4 (&acc)[2][2][4][2], const Unit& u, int wr, int wc, int fr, int fq) const {
;     ...
; #pragma unroll
;         for (int ai = 0; ai < 2; ++ai)
; #pragma unroll
;             for (int m = 0; m < 4; ++m) { const int rl = ai * HALF + wr * 64 + m * 16 + fr; const float rs = rstab[rl]; float* orow = out + (size_t)(u.pm * BM + rl) * D + col0;
; #pragma unroll
;                 for (int bj = 0; bj < 2; ++bj) { *(f32x4*)(orow + bj * HALF) = acc[ai][bj][m][0] * gg[bj][0] * rs; *(f32x4*)(orow + bj * HALF + 4) = acc[ai][bj][m][1] * gg[bj][1] * rs; } }
	v_pk_mul_f32 v[72:73], v[96:97], v[82:83] op_sel_hi:[1,0]
	v_pk_mul_f32 v[70:71], v[98:99], v[82:83] op_sel_hi:[1,0]
	v_pk_mul_f32 v[68:69], v[68:69], v[82:83] op_sel_hi:[1,0]
	v_pk_mul_f32 v[66:67], v[66:67], v[82:83] op_sel_hi:[1,0]
	v_pk_mul_f32 v[76:77], v[76:77], v[82:83] op_sel_hi:[1,0]
	v_pk_mul_f32 v[74:75], v[74:75], v[82:83] op_sel_hi:[1,0]
	v_pk_mul_f32 v[80:81], v[78:79], v[82:83] op_sel_hi:[1,0]
	v_pk_mul_f32 v[78:79], v[84:85], v[82:83] op_sel_hi:[1,0]
	s_nop 1
	v_permlane32_swap_b32_e32 v74, v70
	v_permlane32_swap_b32_e32 v75, v71
	v_permlane32_swap_b32_e32 v76, v72
	v_permlane32_swap_b32_e32 v77, v73
	v_permlane32_swap_b32_e32 v66, v78
	v_permlane32_swap_b32_e32 v67, v79
	v_permlane32_swap_b32_e32 v68, v80
	v_permlane32_swap_b32_e32 v69, v81
	flat_store_dwordx4 v[154:155], v[74:77]
	flat_store_dwordx4 v[154:155], v[70:73] offset:64
	flat_store_dwordx4 v[154:155], v[66:69] offset:512
	flat_store_dwordx4 v[154:155], v[78:81] offset:576
	ds_read_b32 v66, v241
	v_pk_mul_f32 v[64:65], v[64:65], v[16:17]
	v_add_u32_e32 v68, s51, v213
	v_ashrrev_i32_e32 v69, 31, v68
	v_lshlrev_b64 v[68:69], 12, v[68:69]
	v_lshl_add_u64 v[68:69], s[34:35], 0, v[68:69]
	v_pk_mul_f32 v[62:63], v[62:63], v[14:15]
	v_pk_mul_f32 v[60:61], v[60:61], v[12:13]
	v_pk_mul_f32 v[58:59], v[58:59], v[10:11]
	v_pk_mul_f32 v[56:57], v[56:57], v[8:9]
	v_pk_mul_f32 v[54:55], v[54:55], v[6:7]
	v_pk_mul_f32 v[52:53], v[52:53], v[4:5]
	v_pk_mul_f32 v[50:51], v[50:51], v[2:3]
	v_lshl_add_u64 v[68:69], v[68:69], 0, v[146:147]
	s_waitcnt lgkmcnt(0)
	v_pk_mul_f32 v[64:65], v[64:65], v[66:67] op_sel_hi:[1,0]
	v_pk_mul_f32 v[62:63], v[62:63], v[66:67] op_sel_hi:[1,0]
	v_pk_mul_f32 v[60:61], v[60:61], v[66:67] op_sel_hi:[1,0]
	v_pk_mul_f32 v[58:59], v[58:59], v[66:67] op_sel_hi:[1,0]
	v_pk_mul_f32 v[56:57], v[56:57], v[66:67] op_sel_hi:[1,0]
	v_pk_mul_f32 v[54:55], v[54:55], v[66:67] op_sel_hi:[1,0]
	v_pk_mul_f32 v[52:53], v[52:53], v[66:67] op_sel_hi:[1,0]
	v_pk_mul_f32 v[50:51], v[50:51], v[66:67] op_sel_hi:[1,0]
	s_nop 1
	v_permlane32_swap_b32_e32 v58, v62
	v_permlane32_swap_b32_e32 v59, v63
	v_permlane32_swap_b32_e32 v60, v64
	v_permlane32_swap_b32_e32 v61, v65
	v_permlane32_swap_b32_e32 v50, v54
	v_permlane32_swap_b32_e32 v51, v55
	v_permlane32_swap_b32_e32 v52, v56
	v_permlane32_swap_b32_e32 v53, v57
	flat_store_dwordx4 v[68:69], v[58:61]
	flat_store_dwordx4 v[68:69], v[62:65] offset:64
	flat_store_dwordx4 v[68:69], v[50:53] offset:512
	flat_store_dwordx4 v[68:69], v[54:57] offset:576
	ds_read_b32 v50, v242
	v_pk_mul_f32 v[48:49], v[48:49], v[16:17]
	v_add_u32_e32 v52, s51, v214
	v_ashrrev_i32_e32 v53, 31, v52
	v_lshlrev_b64 v[52:53], 12, v[52:53]
	v_lshl_add_u64 v[52:53], s[34:35], 0, v[52:53]
	v_pk_mul_f32 v[46:47], v[46:47], v[14:15]
	v_pk_mul_f32 v[44:45], v[44:45], v[12:13]
	v_pk_mul_f32 v[42:43], v[42:43], v[10:11]
	v_pk_mul_f32 v[40:41], v[40:41], v[8:9]
	v_pk_mul_f32 v[38:39], v[38:39], v[6:7]
	v_pk_mul_f32 v[36:37], v[36:37], v[4:5]
	v_pk_mul_f32 v[34:35], v[34:35], v[2:3]
	v_lshl_add_u64 v[52:53], v[52:53], 0, v[146:147]
	s_waitcnt lgkmcnt(0)
; #define PG8_BAR __builtin_amdgcn_s_barrier()
;     __device__ __forceinline__ void operator()(f32x4 (&acc)[2][2][4][2], const Unit& u, int wr, int wc, int fr, int fq) const {
;     ...
; #pragma unroll
;         for (int ai = 0; ai < 2; ++ai)
; #pragma unroll
;             for (int m = 0; m < 4; ++m) { const int rl = ai * HALF + wr * 64 + m * 16 + fr; const float rs = rstab[rl]; float* orow = out + (size_t)(u.pm * BM + rl) * D + col0;
; #pragma unroll
;                 for (int bj = 0; bj < 2; ++bj) { *(f32x4*)(orow + bj * HALF) = acc[ai][bj][m][0] * gg[bj][0] * rs; *(f32x4*)(orow + bj * HALF + 4) = acc[ai][bj][m][1] * gg[bj][1] * rs; } }
; template <class Epi, bool ALIGN_EPI>
; __device__ __forceinline__ void gemm_phase(LAS unsigned char* lds, const Gemm g, const StaticOrder& S, const Epi& E) {
;     ...
;         if constexpr (ALIGN_EPI) { if (wr == 0) PG8_BAR; }
;         E(acc, cur, wr, wc, fr, fq);
;         if (!has_next) break;
; #pragma unroll
;         for (int a = 0; a < 2; ++a)
; #pragma unroll
;             for (int b = 0; b < 2; ++b)
; #pragma unroll
;                 for (int m = 0; m < 4; ++m)
; #pragma unroll
;                     for (int n = 0; n < 2; ++n) acc[a][b][m][n] = (f32x4){0.f, 0.f, 0.f, 0.f};
;         cur = nxt; cA = nA; cB = nB; ++ui;
;         if constexpr (ALIGN_EPI) { if (wr == 1) PG8_BAR; }
;     }
	v_pk_mul_f32 v[48:49], v[48:49], v[50:51] op_sel_hi:[1,0]
	v_pk_mul_f32 v[46:47], v[46:47], v[50:51] op_sel_hi:[1,0]
	v_pk_mul_f32 v[44:45], v[44:45], v[50:51] op_sel_hi:[1,0]
	v_pk_mul_f32 v[42:43], v[42:43], v[50:51] op_sel_hi:[1,0]
	v_pk_mul_f32 v[40:41], v[40:41], v[50:51] op_sel_hi:[1,0]
	v_pk_mul_f32 v[38:39], v[38:39], v[50:51] op_sel_hi:[1,0]
	v_pk_mul_f32 v[36:37], v[36:37], v[50:51] op_sel_hi:[1,0]
	v_pk_mul_f32 v[34:35], v[34:35], v[50:51] op_sel_hi:[1,0]
	s_nop 1
	v_permlane32_swap_b32_e32 v42, v46
	v_permlane32_swap_b32_e32 v43, v47
	v_permlane32_swap_b32_e32 v44, v48
	v_permlane32_swap_b32_e32 v45, v49
	v_permlane32_swap_b32_e32 v34, v38
	v_permlane32_swap_b32_e32 v35, v39
	v_permlane32_swap_b32_e32 v36, v40
	v_permlane32_swap_b32_e32 v37, v41
	flat_store_dwordx4 v[52:53], v[42:45]
	flat_store_dwordx4 v[52:53], v[46:49] offset:64
	flat_store_dwordx4 v[52:53], v[34:37] offset:512
	flat_store_dwordx4 v[52:53], v[38:41] offset:576
	ds_read_b32 v34, v243
	v_pk_mul_f32 v[32:33], v[32:33], v[16:17]
	v_add_u32_e32 v36, s51, v215
	v_ashrrev_i32_e32 v37, 31, v36
	v_lshlrev_b64 v[36:37], 12, v[36:37]
	v_lshl_add_u64 v[36:37], s[34:35], 0, v[36:37]
	v_pk_mul_f32 v[30:31], v[30:31], v[14:15]
	v_pk_mul_f32 v[28:29], v[28:29], v[12:13]
	v_pk_mul_f32 v[26:27], v[26:27], v[10:11]
	v_pk_mul_f32 v[24:25], v[24:25], v[8:9]
	v_pk_mul_f32 v[22:23], v[22:23], v[6:7]
	v_pk_mul_f32 v[20:21], v[20:21], v[4:5]
	v_pk_mul_f32 v[18:19], v[18:19], v[2:3]
	v_lshl_add_u64 v[36:37], v[36:37], 0, v[146:147]
	s_waitcnt lgkmcnt(0)
	v_pk_mul_f32 v[32:33], v[32:33], v[34:35] op_sel_hi:[1,0]
	v_pk_mul_f32 v[30:31], v[30:31], v[34:35] op_sel_hi:[1,0]
	v_pk_mul_f32 v[28:29], v[28:29], v[34:35] op_sel_hi:[1,0]
	v_pk_mul_f32 v[26:27], v[26:27], v[34:35] op_sel_hi:[1,0]
	v_pk_mul_f32 v[24:25], v[24:25], v[34:35] op_sel_hi:[1,0]
	v_pk_mul_f32 v[22:23], v[22:23], v[34:35] op_sel_hi:[1,0]
	v_pk_mul_f32 v[20:21], v[20:21], v[34:35] op_sel_hi:[1,0]
	v_pk_mul_f32 v[18:19], v[18:19], v[34:35] op_sel_hi:[1,0]
	s_nop 1
	v_permlane32_swap_b32_e32 v26, v30
	v_permlane32_swap_b32_e32 v27, v31
	v_permlane32_swap_b32_e32 v28, v32
	v_permlane32_swap_b32_e32 v29, v33
	v_permlane32_swap_b32_e32 v18, v22
	v_permlane32_swap_b32_e32 v19, v23
	v_permlane32_swap_b32_e32 v20, v24
	v_permlane32_swap_b32_e32 v21, v25
	flat_store_dwordx4 v[36:37], v[26:29]
	flat_store_dwordx4 v[36:37], v[30:33] offset:64
	flat_store_dwordx4 v[36:37], v[18:21] offset:512
	flat_store_dwordx4 v[36:37], v[22:25] offset:576
	ds_read_b32 v18, v244
	v_pk_mul_f32 v[16:17], v[132:133], v[16:17]
	v_add_u32_e32 v20, s51, v216
	v_ashrrev_i32_e32 v21, 31, v20
	v_lshlrev_b64 v[20:21], 12, v[20:21]
	v_lshl_add_u64 v[20:21], s[34:35], 0, v[20:21]
	v_pk_mul_f32 v[14:15], v[136:137], v[14:15]
	v_pk_mul_f32 v[12:13], v[130:131], v[12:13]
	v_pk_mul_f32 v[10:11], v[134:135], v[10:11]
	v_pk_mul_f32 v[8:9], v[138:139], v[8:9]
	v_pk_mul_f32 v[6:7], v[142:143], v[6:7]
	v_pk_mul_f32 v[4:5], v[140:141], v[4:5]
	v_pk_mul_f32 v[2:3], v[144:145], v[2:3]
	v_lshl_add_u64 v[20:21], v[20:21], 0, v[146:147]
	s_waitcnt lgkmcnt(0)
	v_pk_mul_f32 v[16:17], v[16:17], v[18:19] op_sel_hi:[1,0]
	v_pk_mul_f32 v[14:15], v[14:15], v[18:19] op_sel_hi:[1,0]
	v_pk_mul_f32 v[12:13], v[12:13], v[18:19] op_sel_hi:[1,0]
	v_pk_mul_f32 v[10:11], v[10:11], v[18:19] op_sel_hi:[1,0]
	v_pk_mul_f32 v[8:9], v[8:9], v[18:19] op_sel_hi:[1,0]
	v_pk_mul_f32 v[6:7], v[6:7], v[18:19] op_sel_hi:[1,0]
	v_pk_mul_f32 v[4:5], v[4:5], v[18:19] op_sel_hi:[1,0]
	v_pk_mul_f32 v[2:3], v[2:3], v[18:19] op_sel_hi:[1,0]
	s_nop 1
	v_permlane32_swap_b32_e32 v10, v14
	v_permlane32_swap_b32_e32 v11, v15
	v_permlane32_swap_b32_e32 v12, v16
	v_permlane32_swap_b32_e32 v13, v17
	v_permlane32_swap_b32_e32 v2, v6
	v_permlane32_swap_b32_e32 v3, v7
	v_permlane32_swap_b32_e32 v4, v8
	v_permlane32_swap_b32_e32 v5, v9
	flat_store_dwordx4 v[20:21], v[10:13]
	flat_store_dwordx4 v[20:21], v[14:17] offset:64
	flat_store_dwordx4 v[20:21], v[2:5] offset:512
	flat_store_dwordx4 v[20:21], v[6:9] offset:576
	s_cbranch_vccnz .LBB0_189
	v_readlane_b32 s4, v255, 2
	v_readlane_b32 s5, v255, 3
	s_andn2_b64 vcc, exec, s[4:5]
	s_cbranch_vccnz .LBB0_188
	s_barrier
	s_branch .LBB0_188
